# EpiPart (ctx split-K partials): n0/n1 halves swapped between lanes fr<8 and fr>=8 so each 16-byte store covers 8 rows x 128 B (full lines)
# speedup vs baseline: 1.0063x; 1.0063x over previous
;     __device__ __forceinline__ void operator()(const f32x4 (&acc)[2][2][4][2], const pg8::Unit& u, int wr, int wc, int fr, int fq) const {
;         float* outp = part + ((size_t)u.kc * MC + (size_t)(u.pm * 256 - ML)) * DM;
;         const int col0 = u.pn * 256 + wc * 32 + 4 * fq;
; #pragma unroll
;         for (int ai = 0; ai < 2; ++ai)
; #pragma unroll
;             for (int m = 0; m < 4; ++m) { float* rp = outp + (size_t)(wr * 64 + fr + ai * 128 + m * 16) * DM + col0;
; #pragma unroll
;                 for (int bj = 0; bj < 2; ++bj)
; #pragma unroll
;                     for (int n = 0; n < 2; ++n) *(f32x4*)(rp + bj * 128 + n * 16) = acc[ai][bj][m][n]; }
;     }
.Lkpeel_exit_288:
	s_lshl_b32 s20, s45, 8
	s_ashr_i32 s3, s2, 31
	s_ashr_i32 s21, s20, 31
	s_lshl_b64 s[20:21], s[20:21], 12
	s_lshl_b64 s[2:3], s[2:3], 23
	s_add_u32 s2, s48, s2
	s_addc_u32 s3, s49, s3
	s_add_u32 s2, s2, s20
	v_lshl_or_b32 v156, s42, 8, v153
	s_addc_u32 s3, s3, s21
	v_ashrrev_i32_e32 v157, 31, v156
	v_lshl_add_u64 v[156:157], v[156:157], 2, s[2:3]
	s_brev_b32 s2, 31
	s_mov_b32 s3, -1
	v_lshl_add_u64 v[156:157], v[156:157], 0, s[2:3]
	v_and_b32_e32 v166, 8, v220
	v_mul_i32_i24_e32 v166, 0xfffff008, v166
	v_mov_b32_e32 v168, 0x8000
	v_mov_b32_e32 v169, 0
	v_ashrrev_i32_e32 v167, 31, v166
	v_lshl_add_u64 v[156:157], v[156:157], 0, v[166:167]
	v_mov_b32_dpp v160, v126 row_ror:8 row_mask:0xf bank_mask:0x3
	v_mov_b32_dpp v161, v127 row_ror:8 row_mask:0xf bank_mask:0x3
	v_mov_b32_dpp v162, v128 row_ror:8 row_mask:0xf bank_mask:0x3
	v_mov_b32_dpp v163, v129 row_ror:8 row_mask:0xf bank_mask:0x3
	v_mov_b32_dpp v126, v122 row_ror:8 row_mask:0xf bank_mask:0xc
	v_mov_b32_dpp v127, v123 row_ror:8 row_mask:0xf bank_mask:0xc
	v_mov_b32_dpp v128, v124 row_ror:8 row_mask:0xf bank_mask:0xc
	v_mov_b32_dpp v129, v125 row_ror:8 row_mask:0xf bank_mask:0xc
	v_mov_b32_dpp v122, v160 quad_perm:[0,1,2,3] row_mask:0xf bank_mask:0x3
	v_mov_b32_dpp v123, v161 quad_perm:[0,1,2,3] row_mask:0xf bank_mask:0x3
	v_mov_b32_dpp v124, v162 quad_perm:[0,1,2,3] row_mask:0xf bank_mask:0x3
	v_mov_b32_dpp v125, v163 quad_perm:[0,1,2,3] row_mask:0xf bank_mask:0x3
	v_mov_b32_dpp v160, v102 row_ror:8 row_mask:0xf bank_mask:0x3
	v_mov_b32_dpp v161, v103 row_ror:8 row_mask:0xf bank_mask:0x3
	v_mov_b32_dpp v162, v104 row_ror:8 row_mask:0xf bank_mask:0x3
	v_mov_b32_dpp v163, v105 row_ror:8 row_mask:0xf bank_mask:0x3
	v_mov_b32_dpp v102, v94 row_ror:8 row_mask:0xf bank_mask:0xc
	v_mov_b32_dpp v103, v95 row_ror:8 row_mask:0xf bank_mask:0xc
	v_mov_b32_dpp v104, v96 row_ror:8 row_mask:0xf bank_mask:0xc
	v_mov_b32_dpp v105, v97 row_ror:8 row_mask:0xf bank_mask:0xc
	v_mov_b32_dpp v94, v160 quad_perm:[0,1,2,3] row_mask:0xf bank_mask:0x3
	v_mov_b32_dpp v95, v161 quad_perm:[0,1,2,3] row_mask:0xf bank_mask:0x3
	v_mov_b32_dpp v96, v162 quad_perm:[0,1,2,3] row_mask:0xf bank_mask:0x3
	v_mov_b32_dpp v97, v163 quad_perm:[0,1,2,3] row_mask:0xf bank_mask:0x3
	v_lshl_add_u64 v[158:159], v[156:157], 0, v[132:133]
	v_lshl_add_u64 v[164:165], v[158:159], 0, v[168:169]
	global_store_dwordx4 v[158:159], v[126:129], off
	global_store_dwordx4 v[164:165], v[122:125], off
	global_store_dwordx4 v[158:159], v[102:105], off offset:512
	global_store_dwordx4 v[164:165], v[94:97], off offset:512
	s_and_b64 vcc, exec, s[6:7]
	s_mov_b32 s2, s56
	v_mov_b32_dpp v160, v118 row_ror:8 row_mask:0xf bank_mask:0x3
	v_mov_b32_dpp v161, v119 row_ror:8 row_mask:0xf bank_mask:0x3
	v_mov_b32_dpp v162, v120 row_ror:8 row_mask:0xf bank_mask:0x3
	v_mov_b32_dpp v163, v121 row_ror:8 row_mask:0xf bank_mask:0x3
	v_mov_b32_dpp v118, v114 row_ror:8 row_mask:0xf bank_mask:0xc
	v_mov_b32_dpp v119, v115 row_ror:8 row_mask:0xf bank_mask:0xc
	v_mov_b32_dpp v120, v116 row_ror:8 row_mask:0xf bank_mask:0xc
	v_mov_b32_dpp v121, v117 row_ror:8 row_mask:0xf bank_mask:0xc
	v_mov_b32_dpp v114, v160 quad_perm:[0,1,2,3] row_mask:0xf bank_mask:0x3
	v_mov_b32_dpp v115, v161 quad_perm:[0,1,2,3] row_mask:0xf bank_mask:0x3
	v_mov_b32_dpp v116, v162 quad_perm:[0,1,2,3] row_mask:0xf bank_mask:0x3
	v_mov_b32_dpp v117, v163 quad_perm:[0,1,2,3] row_mask:0xf bank_mask:0x3
	v_mov_b32_dpp v160, v86 row_ror:8 row_mask:0xf bank_mask:0x3
	v_mov_b32_dpp v161, v87 row_ror:8 row_mask:0xf bank_mask:0x3
	v_mov_b32_dpp v162, v88 row_ror:8 row_mask:0xf bank_mask:0x3
	v_mov_b32_dpp v163, v89 row_ror:8 row_mask:0xf bank_mask:0x3
	v_mov_b32_dpp v86, v82 row_ror:8 row_mask:0xf bank_mask:0xc
	v_mov_b32_dpp v87, v83 row_ror:8 row_mask:0xf bank_mask:0xc
	v_mov_b32_dpp v88, v84 row_ror:8 row_mask:0xf bank_mask:0xc
	v_mov_b32_dpp v89, v85 row_ror:8 row_mask:0xf bank_mask:0xc
	v_mov_b32_dpp v82, v160 quad_perm:[0,1,2,3] row_mask:0xf bank_mask:0x3
	v_mov_b32_dpp v83, v161 quad_perm:[0,1,2,3] row_mask:0xf bank_mask:0x3
	v_mov_b32_dpp v84, v162 quad_perm:[0,1,2,3] row_mask:0xf bank_mask:0x3
	v_mov_b32_dpp v85, v163 quad_perm:[0,1,2,3] row_mask:0xf bank_mask:0x3
	v_lshl_add_u64 v[94:95], v[156:157], 0, v[134:135]
	v_lshl_add_u64 v[96:97], v[94:95], 0, v[168:169]
	global_store_dwordx4 v[94:95], v[118:121], off
	global_store_dwordx4 v[96:97], v[114:117], off
	global_store_dwordx4 v[94:95], v[86:89], off offset:512
	global_store_dwordx4 v[96:97], v[82:85], off offset:512
	s_mov_b32 s42, s57
	s_mov_b32 s45, s59
	v_mov_b32_dpp v160, v110 row_ror:8 row_mask:0xf bank_mask:0x3
	v_mov_b32_dpp v161, v111 row_ror:8 row_mask:0xf bank_mask:0x3
	v_mov_b32_dpp v162, v112 row_ror:8 row_mask:0xf bank_mask:0x3
	v_mov_b32_dpp v163, v113 row_ror:8 row_mask:0xf bank_mask:0x3
	v_mov_b32_dpp v110, v106 row_ror:8 row_mask:0xf bank_mask:0xc
	v_mov_b32_dpp v111, v107 row_ror:8 row_mask:0xf bank_mask:0xc
	v_mov_b32_dpp v112, v108 row_ror:8 row_mask:0xf bank_mask:0xc
	v_mov_b32_dpp v113, v109 row_ror:8 row_mask:0xf bank_mask:0xc
	v_mov_b32_dpp v106, v160 quad_perm:[0,1,2,3] row_mask:0xf bank_mask:0x3
	v_mov_b32_dpp v107, v161 quad_perm:[0,1,2,3] row_mask:0xf bank_mask:0x3
	v_mov_b32_dpp v108, v162 quad_perm:[0,1,2,3] row_mask:0xf bank_mask:0x3
	v_mov_b32_dpp v109, v163 quad_perm:[0,1,2,3] row_mask:0xf bank_mask:0x3
	v_mov_b32_dpp v160, v78 row_ror:8 row_mask:0xf bank_mask:0x3
	v_mov_b32_dpp v161, v79 row_ror:8 row_mask:0xf bank_mask:0x3
	v_mov_b32_dpp v162, v80 row_ror:8 row_mask:0xf bank_mask:0x3
	v_mov_b32_dpp v163, v81 row_ror:8 row_mask:0xf bank_mask:0x3
	v_mov_b32_dpp v78, v74 row_ror:8 row_mask:0xf bank_mask:0xc
;     __device__ __forceinline__ void operator()(const f32x4 (&acc)[2][2][4][2], const pg8::Unit& u, int wr, int wc, int fr, int fq) const {
;         float* outp = part + ((size_t)u.kc * MC + (size_t)(u.pm * 256 - ML)) * DM;
;         const int col0 = u.pn * 256 + wc * 32 + 4 * fq;
; #pragma unroll
;         for (int ai = 0; ai < 2; ++ai)
; #pragma unroll
;             for (int m = 0; m < 4; ++m) { float* rp = outp + (size_t)(wr * 64 + fr + ai * 128 + m * 16) * DM + col0;
; #pragma unroll
;                 for (int bj = 0; bj < 2; ++bj)
; #pragma unroll
;                     for (int n = 0; n < 2; ++n) *(f32x4*)(rp + bj * 128 + n * 16) = acc[ai][bj][m][n]; }
;     }
	v_mov_b32_dpp v79, v75 row_ror:8 row_mask:0xf bank_mask:0xc
	v_mov_b32_dpp v80, v76 row_ror:8 row_mask:0xf bank_mask:0xc
	v_mov_b32_dpp v81, v77 row_ror:8 row_mask:0xf bank_mask:0xc
	v_mov_b32_dpp v74, v160 quad_perm:[0,1,2,3] row_mask:0xf bank_mask:0x3
	v_mov_b32_dpp v75, v161 quad_perm:[0,1,2,3] row_mask:0xf bank_mask:0x3
	v_mov_b32_dpp v76, v162 quad_perm:[0,1,2,3] row_mask:0xf bank_mask:0x3
	v_mov_b32_dpp v77, v163 quad_perm:[0,1,2,3] row_mask:0xf bank_mask:0x3
	v_lshl_add_u64 v[82:83], v[156:157], 0, v[136:137]
	v_lshl_add_u64 v[84:85], v[82:83], 0, v[168:169]
	global_store_dwordx4 v[82:83], v[110:113], off
	global_store_dwordx4 v[84:85], v[106:109], off
	global_store_dwordx4 v[82:83], v[78:81], off offset:512
	global_store_dwordx4 v[84:85], v[74:77], off offset:512
	s_mov_b64 s[22:23], s[16:17]
	s_mov_b64 s[20:21], s[12:13]
	v_mov_b32_dpp v160, v98 row_ror:8 row_mask:0xf bank_mask:0x3
	v_mov_b32_dpp v161, v99 row_ror:8 row_mask:0xf bank_mask:0x3
	v_mov_b32_dpp v162, v100 row_ror:8 row_mask:0xf bank_mask:0x3
	v_mov_b32_dpp v163, v101 row_ror:8 row_mask:0xf bank_mask:0x3
	v_mov_b32_dpp v98, v90 row_ror:8 row_mask:0xf bank_mask:0xc
	v_mov_b32_dpp v99, v91 row_ror:8 row_mask:0xf bank_mask:0xc
	v_mov_b32_dpp v100, v92 row_ror:8 row_mask:0xf bank_mask:0xc
	v_mov_b32_dpp v101, v93 row_ror:8 row_mask:0xf bank_mask:0xc
	v_mov_b32_dpp v90, v160 quad_perm:[0,1,2,3] row_mask:0xf bank_mask:0x3
	v_mov_b32_dpp v91, v161 quad_perm:[0,1,2,3] row_mask:0xf bank_mask:0x3
	v_mov_b32_dpp v92, v162 quad_perm:[0,1,2,3] row_mask:0xf bank_mask:0x3
	v_mov_b32_dpp v93, v163 quad_perm:[0,1,2,3] row_mask:0xf bank_mask:0x3
	v_mov_b32_dpp v160, v70 row_ror:8 row_mask:0xf bank_mask:0x3
	v_mov_b32_dpp v161, v71 row_ror:8 row_mask:0xf bank_mask:0x3
	v_mov_b32_dpp v162, v72 row_ror:8 row_mask:0xf bank_mask:0x3
	v_mov_b32_dpp v163, v73 row_ror:8 row_mask:0xf bank_mask:0x3
	v_mov_b32_dpp v70, v66 row_ror:8 row_mask:0xf bank_mask:0xc
	v_mov_b32_dpp v71, v67 row_ror:8 row_mask:0xf bank_mask:0xc
	v_mov_b32_dpp v72, v68 row_ror:8 row_mask:0xf bank_mask:0xc
	v_mov_b32_dpp v73, v69 row_ror:8 row_mask:0xf bank_mask:0xc
	v_mov_b32_dpp v66, v160 quad_perm:[0,1,2,3] row_mask:0xf bank_mask:0x3
	v_mov_b32_dpp v67, v161 quad_perm:[0,1,2,3] row_mask:0xf bank_mask:0x3
	v_mov_b32_dpp v68, v162 quad_perm:[0,1,2,3] row_mask:0xf bank_mask:0x3
	v_mov_b32_dpp v69, v163 quad_perm:[0,1,2,3] row_mask:0xf bank_mask:0x3
	v_lshl_add_u64 v[74:75], v[156:157], 0, v[138:139]
	v_lshl_add_u64 v[76:77], v[74:75], 0, v[168:169]
	global_store_dwordx4 v[74:75], v[98:101], off
	global_store_dwordx4 v[76:77], v[90:93], off
	global_store_dwordx4 v[74:75], v[70:73], off offset:512
	global_store_dwordx4 v[76:77], v[66:69], off offset:512
	s_nop 1
	v_mov_b32_dpp v160, v62 row_ror:8 row_mask:0xf bank_mask:0x3
	v_mov_b32_dpp v161, v63 row_ror:8 row_mask:0xf bank_mask:0x3
	v_mov_b32_dpp v162, v64 row_ror:8 row_mask:0xf bank_mask:0x3
	v_mov_b32_dpp v163, v65 row_ror:8 row_mask:0xf bank_mask:0x3
	v_mov_b32_dpp v62, v58 row_ror:8 row_mask:0xf bank_mask:0xc
	v_mov_b32_dpp v63, v59 row_ror:8 row_mask:0xf bank_mask:0xc
	v_mov_b32_dpp v64, v60 row_ror:8 row_mask:0xf bank_mask:0xc
	v_mov_b32_dpp v65, v61 row_ror:8 row_mask:0xf bank_mask:0xc
	v_mov_b32_dpp v58, v160 quad_perm:[0,1,2,3] row_mask:0xf bank_mask:0x3
	v_mov_b32_dpp v59, v161 quad_perm:[0,1,2,3] row_mask:0xf bank_mask:0x3
	v_mov_b32_dpp v60, v162 quad_perm:[0,1,2,3] row_mask:0xf bank_mask:0x3
	v_mov_b32_dpp v61, v163 quad_perm:[0,1,2,3] row_mask:0xf bank_mask:0x3
	v_mov_b32_dpp v160, v36 row_ror:8 row_mask:0xf bank_mask:0x3
	v_mov_b32_dpp v161, v37 row_ror:8 row_mask:0xf bank_mask:0x3
	v_mov_b32_dpp v162, v38 row_ror:8 row_mask:0xf bank_mask:0x3
	v_mov_b32_dpp v163, v39 row_ror:8 row_mask:0xf bank_mask:0x3
	v_mov_b32_dpp v36, v28 row_ror:8 row_mask:0xf bank_mask:0xc
	v_mov_b32_dpp v37, v29 row_ror:8 row_mask:0xf bank_mask:0xc
	v_mov_b32_dpp v38, v30 row_ror:8 row_mask:0xf bank_mask:0xc
	v_mov_b32_dpp v39, v31 row_ror:8 row_mask:0xf bank_mask:0xc
	v_mov_b32_dpp v28, v160 quad_perm:[0,1,2,3] row_mask:0xf bank_mask:0x3
	v_mov_b32_dpp v29, v161 quad_perm:[0,1,2,3] row_mask:0xf bank_mask:0x3
	v_mov_b32_dpp v30, v162 quad_perm:[0,1,2,3] row_mask:0xf bank_mask:0x3
	v_mov_b32_dpp v31, v163 quad_perm:[0,1,2,3] row_mask:0xf bank_mask:0x3
	v_lshl_add_u64 v[66:67], v[156:157], 0, v[140:141]
	v_lshl_add_u64 v[68:69], v[66:67], 0, v[168:169]
	global_store_dwordx4 v[66:67], v[62:65], off
	global_store_dwordx4 v[68:69], v[58:61], off
	global_store_dwordx4 v[66:67], v[36:39], off offset:512
	global_store_dwordx4 v[68:69], v[28:31], off offset:512
	s_nop 1
	v_mov_b32_dpp v160, v54 row_ror:8 row_mask:0xf bank_mask:0x3
	v_mov_b32_dpp v161, v55 row_ror:8 row_mask:0xf bank_mask:0x3
	v_mov_b32_dpp v162, v56 row_ror:8 row_mask:0xf bank_mask:0x3
	v_mov_b32_dpp v163, v57 row_ror:8 row_mask:0xf bank_mask:0x3
	v_mov_b32_dpp v54, v50 row_ror:8 row_mask:0xf bank_mask:0xc
	v_mov_b32_dpp v55, v51 row_ror:8 row_mask:0xf bank_mask:0xc
	v_mov_b32_dpp v56, v52 row_ror:8 row_mask:0xf bank_mask:0xc
	v_mov_b32_dpp v57, v53 row_ror:8 row_mask:0xf bank_mask:0xc
	v_mov_b32_dpp v50, v160 quad_perm:[0,1,2,3] row_mask:0xf bank_mask:0x3
	v_mov_b32_dpp v51, v161 quad_perm:[0,1,2,3] row_mask:0xf bank_mask:0x3
; #define PG8_WAIT_V(n) asm volatile("s_waitcnt vmcnt(" #n ")" ::: "memory")
; #define PG8_BAR __builtin_amdgcn_s_barrier()
; template <class Epi, class Sched>
; __device__ __forceinline__ void gemm_phase(PG8_LAS unsigned char* lds, const Gemm g, const Sched& S, const Epi& E) {
;     ...
;         if (!has_next) break;
; #pragma unroll
;         for (int a = 0; a < 2; ++a)
; #pragma unroll
;             for (int b = 0; b < 2; ++b)
; #pragma unroll
;                 for (int m = 0; m < 4; ++m)
; #pragma unroll
;                     for (int n = 0; n < 2; ++n) acc[a][b][m][n] = (f32x4){0.f, 0.f, 0.f, 0.f};
;         cur = nxt; cA = nA; cB = nB; ++ui;
;     }
;     PG8_WAIT_V(0);
;     if (wr == 0) PG8_BAR;
;     PG8_BAR;
;     __device__ __forceinline__ void operator()(const f32x4 (&acc)[2][2][4][2], const pg8::Unit& u, int wr, int wc, int fr, int fq) const {
;         float* outp = part + ((size_t)u.kc * MC + (size_t)(u.pm * 256 - ML)) * DM;
;         const int col0 = u.pn * 256 + wc * 32 + 4 * fq;
; #pragma unroll
;         for (int ai = 0; ai < 2; ++ai)
; #pragma unroll
;             for (int m = 0; m < 4; ++m) { float* rp = outp + (size_t)(wr * 64 + fr + ai * 128 + m * 16) * DM + col0;
; #pragma unroll
;                 for (int bj = 0; bj < 2; ++bj)
; #pragma unroll
;                     for (int n = 0; n < 2; ++n) *(f32x4*)(rp + bj * 128 + n * 16) = acc[ai][bj][m][n]; }
;     }
	v_mov_b32_dpp v52, v162 quad_perm:[0,1,2,3] row_mask:0xf bank_mask:0x3
	v_mov_b32_dpp v53, v163 quad_perm:[0,1,2,3] row_mask:0xf bank_mask:0x3
	v_mov_b32_dpp v160, v20 row_ror:8 row_mask:0xf bank_mask:0x3
	v_mov_b32_dpp v161, v21 row_ror:8 row_mask:0xf bank_mask:0x3
	v_mov_b32_dpp v162, v22 row_ror:8 row_mask:0xf bank_mask:0x3
	v_mov_b32_dpp v163, v23 row_ror:8 row_mask:0xf bank_mask:0x3
	v_mov_b32_dpp v20, v16 row_ror:8 row_mask:0xf bank_mask:0xc
	v_mov_b32_dpp v21, v17 row_ror:8 row_mask:0xf bank_mask:0xc
	v_mov_b32_dpp v22, v18 row_ror:8 row_mask:0xf bank_mask:0xc
	v_mov_b32_dpp v23, v19 row_ror:8 row_mask:0xf bank_mask:0xc
	v_mov_b32_dpp v16, v160 quad_perm:[0,1,2,3] row_mask:0xf bank_mask:0x3
	v_mov_b32_dpp v17, v161 quad_perm:[0,1,2,3] row_mask:0xf bank_mask:0x3
	v_mov_b32_dpp v18, v162 quad_perm:[0,1,2,3] row_mask:0xf bank_mask:0x3
	v_mov_b32_dpp v19, v163 quad_perm:[0,1,2,3] row_mask:0xf bank_mask:0x3
	v_lshl_add_u64 v[28:29], v[156:157], 0, v[142:143]
	v_lshl_add_u64 v[30:31], v[28:29], 0, v[168:169]
	global_store_dwordx4 v[28:29], v[54:57], off
	global_store_dwordx4 v[30:31], v[50:53], off
	global_store_dwordx4 v[28:29], v[20:23], off offset:512
	global_store_dwordx4 v[30:31], v[16:19], off offset:512
	s_nop 1
	v_mov_b32_dpp v160, v44 row_ror:8 row_mask:0xf bank_mask:0x3
	v_mov_b32_dpp v161, v45 row_ror:8 row_mask:0xf bank_mask:0x3
	v_mov_b32_dpp v162, v46 row_ror:8 row_mask:0xf bank_mask:0x3
	v_mov_b32_dpp v163, v47 row_ror:8 row_mask:0xf bank_mask:0x3
	v_mov_b32_dpp v44, v40 row_ror:8 row_mask:0xf bank_mask:0xc
	v_mov_b32_dpp v45, v41 row_ror:8 row_mask:0xf bank_mask:0xc
	v_mov_b32_dpp v46, v42 row_ror:8 row_mask:0xf bank_mask:0xc
	v_mov_b32_dpp v47, v43 row_ror:8 row_mask:0xf bank_mask:0xc
	v_mov_b32_dpp v40, v160 quad_perm:[0,1,2,3] row_mask:0xf bank_mask:0x3
	v_mov_b32_dpp v41, v161 quad_perm:[0,1,2,3] row_mask:0xf bank_mask:0x3
	v_mov_b32_dpp v42, v162 quad_perm:[0,1,2,3] row_mask:0xf bank_mask:0x3
	v_mov_b32_dpp v43, v163 quad_perm:[0,1,2,3] row_mask:0xf bank_mask:0x3
	v_mov_b32_dpp v160, v12 row_ror:8 row_mask:0xf bank_mask:0x3
	v_mov_b32_dpp v161, v13 row_ror:8 row_mask:0xf bank_mask:0x3
	v_mov_b32_dpp v162, v14 row_ror:8 row_mask:0xf bank_mask:0x3
	v_mov_b32_dpp v163, v15 row_ror:8 row_mask:0xf bank_mask:0x3
	v_mov_b32_dpp v12, v8 row_ror:8 row_mask:0xf bank_mask:0xc
	v_mov_b32_dpp v13, v9 row_ror:8 row_mask:0xf bank_mask:0xc
	v_mov_b32_dpp v14, v10 row_ror:8 row_mask:0xf bank_mask:0xc
	v_mov_b32_dpp v15, v11 row_ror:8 row_mask:0xf bank_mask:0xc
	v_mov_b32_dpp v8, v160 quad_perm:[0,1,2,3] row_mask:0xf bank_mask:0x3
	v_mov_b32_dpp v9, v161 quad_perm:[0,1,2,3] row_mask:0xf bank_mask:0x3
	v_mov_b32_dpp v10, v162 quad_perm:[0,1,2,3] row_mask:0xf bank_mask:0x3
	v_mov_b32_dpp v11, v163 quad_perm:[0,1,2,3] row_mask:0xf bank_mask:0x3
	v_lshl_add_u64 v[16:17], v[156:157], 0, v[144:145]
	v_lshl_add_u64 v[18:19], v[16:17], 0, v[168:169]
	global_store_dwordx4 v[16:17], v[44:47], off
	global_store_dwordx4 v[18:19], v[40:43], off
	global_store_dwordx4 v[16:17], v[12:15], off offset:512
	global_store_dwordx4 v[18:19], v[8:11], off offset:512
	s_nop 1
	v_mov_b32_dpp v160, v32 row_ror:8 row_mask:0xf bank_mask:0x3
	v_mov_b32_dpp v161, v33 row_ror:8 row_mask:0xf bank_mask:0x3
	v_mov_b32_dpp v162, v34 row_ror:8 row_mask:0xf bank_mask:0x3
	v_mov_b32_dpp v163, v35 row_ror:8 row_mask:0xf bank_mask:0x3
	v_mov_b32_dpp v32, v24 row_ror:8 row_mask:0xf bank_mask:0xc
	v_mov_b32_dpp v33, v25 row_ror:8 row_mask:0xf bank_mask:0xc
	v_mov_b32_dpp v34, v26 row_ror:8 row_mask:0xf bank_mask:0xc
	v_mov_b32_dpp v35, v27 row_ror:8 row_mask:0xf bank_mask:0xc
	v_mov_b32_dpp v24, v160 quad_perm:[0,1,2,3] row_mask:0xf bank_mask:0x3
	v_mov_b32_dpp v25, v161 quad_perm:[0,1,2,3] row_mask:0xf bank_mask:0x3
	v_mov_b32_dpp v26, v162 quad_perm:[0,1,2,3] row_mask:0xf bank_mask:0x3
	v_mov_b32_dpp v27, v163 quad_perm:[0,1,2,3] row_mask:0xf bank_mask:0x3
	v_mov_b32_dpp v160, v4 row_ror:8 row_mask:0xf bank_mask:0x3
	v_mov_b32_dpp v161, v5 row_ror:8 row_mask:0xf bank_mask:0x3
	v_mov_b32_dpp v162, v6 row_ror:8 row_mask:0xf bank_mask:0x3
	v_mov_b32_dpp v163, v7 row_ror:8 row_mask:0xf bank_mask:0x3
	v_mov_b32_dpp v4, v0 row_ror:8 row_mask:0xf bank_mask:0xc
	v_mov_b32_dpp v5, v1 row_ror:8 row_mask:0xf bank_mask:0xc
	v_mov_b32_dpp v6, v2 row_ror:8 row_mask:0xf bank_mask:0xc
	v_mov_b32_dpp v7, v3 row_ror:8 row_mask:0xf bank_mask:0xc
	v_mov_b32_dpp v0, v160 quad_perm:[0,1,2,3] row_mask:0xf bank_mask:0x3
	v_mov_b32_dpp v1, v161 quad_perm:[0,1,2,3] row_mask:0xf bank_mask:0x3
	v_mov_b32_dpp v2, v162 quad_perm:[0,1,2,3] row_mask:0xf bank_mask:0x3
	v_mov_b32_dpp v3, v163 quad_perm:[0,1,2,3] row_mask:0xf bank_mask:0x3
	v_lshl_add_u64 v[8:9], v[156:157], 0, v[146:147]
	v_lshl_add_u64 v[10:11], v[8:9], 0, v[168:169]
	global_store_dwordx4 v[8:9], v[32:35], off
	global_store_dwordx4 v[10:11], v[24:27], off
	global_store_dwordx4 v[8:9], v[4:7], off offset:512
	global_store_dwordx4 v[10:11], v[0:3], off offset:512
	s_cbranch_vccz .LBB0_281
	s_waitcnt vmcnt(0)
	v_readlane_b32 s46, v254, 33
	v_readlane_b32 s48, v254, 35
	s_cmpk_gt_u32 s34, 0xff
	v_readlane_b32 s54, v254, 31
	v_readlane_b32 s47, v254, 34
	v_readlane_b32 s49, v254, 36
	v_readlane_b32 s55, v254, 39
	s_mov_b32 s57, s65
	s_cbranch_scc1 .LBB0_292
	s_barrier
